# mla_prep: prefetch next iteration's q/kv/k_rope rows into L2 at top of each 2-token iteration
# baseline (speedup 1.0000x reference)
; __device__ __forceinline__ unsigned pk2(float lo, float hi) { f32x2 v = {lo, hi}; bf16x2_t b = __builtin_convertvector(v, bf16x2_t); return __builtin_bit_cast(unsigned, b); }
; __device__ __forceinline__ float sum8_dpp(float v) { v += dppf<0xB1>(v); v += dppf<0x4E>(v); v += dppf<0x141>(v); return v; }
; __device__ __forceinline__ void mla_prep(const Ctx& c, const Params& p, int o) {
;     ...
;     for (int tile = c.bid; tile < 512; tile += c.G) { const int m0 = tile * 64;
; #pragma unroll 2
;         for (int q = 0; q < 8; ++q) { const int tt = c.wave * 8 + q, m = m0 + tt; const float rsq = RS[2 * m], rskv = RS[2 * m + 1];
;             float sn_, cs_; { const float rev = (float)pos[m] * invr; const float fr = rev - floorf(rev); sn_ = __builtin_amdgcn_sinf(fr); cs_ = __builtin_amdgcn_cosf(fr); }
;             float cs[2], sn[2];
; #pragma unroll
;             for (int j = 0; j < 2; ++j) { cs[j] = __shfl(cs_, 2 * sub + j); sn[j] = __shfl(sn_, 2 * sub + j); }
;             { bf16_t* qp = QR + (size_t)m * 768 + head * 96; float v[8]; unpack8(*(const u32x4*)(qp + 8 * sub), v);
;               const unsigned r1 = *(const unsigned*)(qp + 64 + 2 * sub), r2 = *(const unsigned*)(qp + 80 + 2 * sub);
;               float x1[2] = {asf(r1 << 16) * rsq, asf(r1 & 0xffff0000u) * rsq}, x2[2] = {asf(r2 << 16) * rsq, asf(r2 & 0xffff0000u) * rsq};
;               float ss = x1[0] * x1[0] + x1[1] * x1[1] + x2[0] * x2[0] + x2[1] * x2[1];
; #pragma unroll
;               for (int i = 0; i < 8; ++i) { v[i] *= rsq; ss += v[i] * v[i]; }
;               const float rn = rsqrtf(sum8_dpp(ss) * (1.f / 96.f) + 1e-6f) ;
; #pragma unroll
;               for (int i = 0; i < 8; ++i) v[i] = v[i] * rn * gqn[i] * QSCALE;
;               float o1[2], o2[2];
; #pragma unroll
;               for (int j = 0; j < 2; ++j) { const float a = x1[j] * rn * gq1[j], bq = x2[j] * rn * gq2[j]; o1[j] = (a * cs[j] - bq * sn[j]) * QSCALE; o2[j] = (bq * cs[j] + a * sn[j]) * QSCALE; }
;               *(u32x4*)(qp + 8 * sub) = pack8(v); *(unsigned*)(qp + 64 + 2 * sub) = pk2(o1[0], o1[1]); *(unsigned*)(qp + 80 + 2 * sub) = pk2(o2[0], o2[1]); }
;             { const bf16_t* kp = KVR + (size_t)m * 1024 + head * 128; float v[8]; unpack8(*(const u32x4*)(kp + 8 * sub), v);
;               const unsigned r1 = *(const unsigned*)(KR + (size_t)m * 32 + 2 * sub), r2 = *(const unsigned*)(KR + (size_t)m * 32 + 16 + 2 * sub);
.LBB0_182:
	s_add_i32 s8, s6, 2
	s_cmp_lg_u32 s25, 12
	s_cbranch_scc1 .Lmp_pf
	s_add_i32 s8, s20, s21
	s_add_i32 s9, s24, s38
	s_cmpk_gt_i32 s9, 0x1ff
	s_cbranch_scc1 .Lmp_nopf
.Lmp_pf:
	v_lshlrev_b32_e32 v80, 4, v164
	s_mul_i32 s2, s8, 0x600
	s_add_u32 s2, s2, 0x1cc00000
	s_add_u32 s2, s22, s2
	s_addc_u32 s3, s23, 0
	global_load_dwordx4 v[84:87], v80, s[2:3]
	global_load_dwordx4 v[88:91], v80, s[2:3] offset:1024
	global_load_dwordx4 v[92:95], v80, s[2:3] offset:2048
	s_lshl_b32 s10, s8, 11
	s_add_u32 s10, s74, s10
	s_addc_u32 s11, s75, 0
	global_load_dwordx4 v[96:99], v80, s[10:11]
	global_load_dwordx4 v[84:87], v80, s[10:11] offset:1024
	global_load_dwordx4 v[88:91], v80, s[10:11] offset:2048
	global_load_dwordx4 v[92:95], v80, s[10:11] offset:3072
	v_lshlrev_b32_e32 v81, 2, v164
	v_and_b32_e32 v81, 0x7c, v81
	s_lshl_b32 s14, s8, 6
	s_add_u32 s14, s14, 0x1c900000
	s_add_u32 s14, s22, s14
	s_addc_u32 s15, s23, 0
	global_load_dword v96, v81, s[14:15]
